# K-loops: the two waits at the end of each load segment (vmcnt(8), lgkmcnt(0)) merged into one s_waitcnt
# baseline (speedup 1.0000x reference)
.LBB0_318:
	ds_read_b128 v[146:149], v194
	ds_read_b128 v[150:153], v194 offset:1024
	ds_read_b128 v[154:157], v194 offset:2048
	ds_read_b128 v[158:161], v194 offset:3072
	ds_read_b128 v[130:133], v194 offset:16384
	ds_read_b128 v[134:137], v194 offset:17408
	ds_read_b128 v[138:141], v194 offset:18432
	ds_read_b128 v[142:145], v194 offset:19456
	s_add_u32 s42, s93, s9
	s_addc_u32 s43, s94, 0
	s_add_u32 s42, s42, 0xffffff80
	s_addc_u32 s43, s43, -1
	s_mov_b32 s74, m0
	s_mov_b32 m0, s65
	s_nop 0
	global_load_lds_dwordx4 v245, s[42:43]
	s_mov_b32 m0, s74
	s_nop 0
	s_mov_b32 s74, m0
	s_mov_b32 m0, s66
	s_nop 0
	global_load_lds_dwordx4 v247, s[42:43]
	s_mov_b32 m0, s74
	s_cmp_eq_u32 s57, s3
	s_cselect_b32 s73, s55, s94
	s_cselect_b32 s72, s54, s93
	s_cselect_b32 s77, s63, s92
	s_cselect_b32 s76, s62, s8
	s_waitcnt lgkmcnt(0)
	ds_read_b128 v[162:165], v252
	ds_read_b128 v[166:169], v252 offset:1024
	ds_read_b128 v[170:173], v252 offset:2048
	ds_read_b128 v[174:177], v252 offset:3072
	ds_read_b128 v[178:181], v252 offset:4096
	ds_read_b128 v[182:185], v252 offset:5120
	ds_read_b128 v[186:189], v252 offset:6144
	ds_read_b128 v[190:193], v252 offset:7168
	s_waitcnt vmcnt(8) lgkmcnt(0)
	s_setprio 1
	s_barrier
	v_mfma_f32_16x16x32_bf16 v[124:127], v[146:149], v[162:165], v[124:127]
	v_mfma_f32_16x16x32_bf16 v[120:123], v[154:157], v[162:165], v[120:123]
	v_mfma_f32_16x16x32_bf16 v[108:111], v[146:149], v[170:173], v[108:111]
	v_mfma_f32_16x16x32_bf16 v[104:107], v[154:157], v[170:173], v[104:107]
	v_mfma_f32_16x16x32_bf16 v[92:95], v[146:149], v[178:181], v[92:95]
	v_mfma_f32_16x16x32_bf16 v[88:91], v[154:157], v[178:181], v[88:91]
	v_mfma_f32_16x16x32_bf16 v[76:79], v[146:149], v[186:189], v[76:79]
	v_mfma_f32_16x16x32_bf16 v[72:75], v[154:157], v[186:189], v[72:75]
	v_mfma_f32_16x16x32_bf16 v[124:127], v[150:153], v[166:169], v[124:127]
	v_mfma_f32_16x16x32_bf16 v[120:123], v[158:161], v[166:169], v[120:123]
	v_mfma_f32_16x16x32_bf16 v[108:111], v[150:153], v[174:177], v[108:111]
	v_mfma_f32_16x16x32_bf16 v[104:107], v[158:161], v[174:177], v[104:107]
	v_mfma_f32_16x16x32_bf16 v[92:95], v[150:153], v[182:185], v[92:95]
	v_mfma_f32_16x16x32_bf16 v[88:91], v[158:161], v[182:185], v[88:91]
	v_mfma_f32_16x16x32_bf16 v[76:79], v[150:153], v[190:193], v[76:79]
	v_mfma_f32_16x16x32_bf16 v[72:75], v[158:161], v[190:193], v[72:75]
	s_setprio 0
	s_setprio 1
	v_mfma_f32_16x16x32_bf16 v[116:119], v[130:133], v[162:165], v[116:119]
	v_mfma_f32_16x16x32_bf16 v[112:115], v[138:141], v[162:165], v[112:115]
	v_mfma_f32_16x16x32_bf16 v[100:103], v[130:133], v[170:173], v[100:103]
	v_mfma_f32_16x16x32_bf16 v[96:99], v[138:141], v[170:173], v[96:99]
	v_mfma_f32_16x16x32_bf16 v[84:87], v[130:133], v[178:181], v[84:87]
	v_mfma_f32_16x16x32_bf16 v[80:83], v[138:141], v[178:181], v[80:83]
	v_mfma_f32_16x16x32_bf16 v[68:71], v[130:133], v[186:189], v[68:71]
	v_mfma_f32_16x16x32_bf16 v[64:67], v[138:141], v[186:189], v[64:67]
	v_mfma_f32_16x16x32_bf16 v[116:119], v[134:137], v[166:169], v[116:119]
	v_mfma_f32_16x16x32_bf16 v[112:115], v[142:145], v[166:169], v[112:115]
	v_mfma_f32_16x16x32_bf16 v[100:103], v[134:137], v[174:177], v[100:103]
	v_mfma_f32_16x16x32_bf16 v[96:99], v[142:145], v[174:177], v[96:99]
	v_mfma_f32_16x16x32_bf16 v[84:87], v[134:137], v[182:185], v[84:87]
	v_mfma_f32_16x16x32_bf16 v[80:83], v[142:145], v[182:185], v[80:83]
	v_mfma_f32_16x16x32_bf16 v[68:71], v[134:137], v[190:193], v[68:71]
	v_mfma_f32_16x16x32_bf16 v[64:67], v[142:145], v[190:193], v[64:67]
	s_setprio 0
	s_barrier
	s_mov_b32 s42, m0
	s_mov_b32 m0, s14
	s_nop 0
	global_load_lds_dwordx4 v246, s[76:77]
	s_mov_b32 m0, s42
	s_add_u32 s74, s76, s9
	s_mov_b32 s42, m0
	s_mov_b32 m0, s15
	s_nop 0
	global_load_lds_dwordx4 v248, s[76:77]
	s_mov_b32 m0, s42
	s_addc_u32 s75, s77, 0
	s_mov_b32 s42, m0
	s_mov_b32 m0, s16
	s_nop 0
	global_load_lds_dwordx4 v246, s[74:75]
	s_mov_b32 m0, s42
	v_cndmask_b32_e64 v128, 0, 1, s[68:69]
	s_mov_b32 s42, m0
	s_mov_b32 m0, s17
	s_nop 0
	global_load_lds_dwordx4 v248, s[74:75]
	s_mov_b32 m0, s42
	s_andn2_b64 vcc, exec, s[68:69]
	s_mov_b32 s42, m0
	s_mov_b32 m0, s11
	s_nop 0
	global_load_lds_dwordx4 v245, s[72:73]
	s_mov_b32 m0, s42
	s_nop 0
	s_mov_b32 s42, m0
	s_mov_b32 m0, s19
	s_nop 0
	global_load_lds_dwordx4 v247, s[72:73]
	s_mov_b32 m0, s42
	ds_read_b128 v[186:189], v252 offset:16384
	ds_read_b128 v[190:193], v252 offset:17408
	ds_read_b128 v[178:181], v252 offset:18432
	ds_read_b128 v[182:185], v252 offset:19456
	ds_read_b128 v[170:173], v252 offset:20480
	ds_read_b128 v[174:177], v252 offset:21504
	ds_read_b128 v[162:165], v252 offset:22528
	ds_read_b128 v[166:169], v252 offset:23552
	v_cmp_ne_u32_e64 s[42:43], 1, v128
	s_waitcnt vmcnt(8) lgkmcnt(0)
	s_barrier
	s_cbranch_vccnz .LBB0_320
	s_setprio 1
	v_mfma_f32_16x16x32_bf16 v[60:63], v[146:149], v[186:189], v[60:63]
	v_mfma_f32_16x16x32_bf16 v[56:59], v[154:157], v[186:189], v[56:59]
	v_mfma_f32_16x16x32_bf16 v[44:47], v[146:149], v[178:181], v[44:47]
	v_mfma_f32_16x16x32_bf16 v[40:43], v[154:157], v[178:181], v[40:43]
	v_mfma_f32_16x16x32_bf16 v[28:31], v[146:149], v[170:173], v[28:31]
	v_mfma_f32_16x16x32_bf16 v[24:27], v[154:157], v[170:173], v[24:27]
	v_mfma_f32_16x16x32_bf16 v[12:15], v[146:149], v[162:165], v[12:15]
	v_mfma_f32_16x16x32_bf16 v[8:11], v[154:157], v[162:165], v[8:11]
	v_mfma_f32_16x16x32_bf16 v[60:63], v[150:153], v[190:193], v[60:63]
	v_mfma_f32_16x16x32_bf16 v[56:59], v[158:161], v[190:193], v[56:59]
	v_mfma_f32_16x16x32_bf16 v[44:47], v[150:153], v[182:185], v[44:47]
	v_mfma_f32_16x16x32_bf16 v[40:43], v[158:161], v[182:185], v[40:43]
	v_mfma_f32_16x16x32_bf16 v[28:31], v[150:153], v[174:177], v[28:31]
	v_mfma_f32_16x16x32_bf16 v[24:27], v[158:161], v[174:177], v[24:27]
	v_mfma_f32_16x16x32_bf16 v[12:15], v[150:153], v[166:169], v[12:15]
	v_mfma_f32_16x16x32_bf16 v[8:11], v[158:161], v[166:169], v[8:11]
	s_setprio 0
	s_setprio 1
	v_mfma_f32_16x16x32_bf16 v[52:55], v[130:133], v[186:189], v[52:55]
	v_mfma_f32_16x16x32_bf16 v[48:51], v[138:141], v[186:189], v[48:51]
	v_mfma_f32_16x16x32_bf16 v[36:39], v[130:133], v[178:181], v[36:39]
	v_mfma_f32_16x16x32_bf16 v[32:35], v[138:141], v[178:181], v[32:35]
	v_mfma_f32_16x16x32_bf16 v[20:23], v[130:133], v[170:173], v[20:23]
	v_mfma_f32_16x16x32_bf16 v[16:19], v[138:141], v[170:173], v[16:19]
	v_mfma_f32_16x16x32_bf16 v[4:7], v[130:133], v[162:165], v[4:7]
	v_mfma_f32_16x16x32_bf16 v[0:3], v[138:141], v[162:165], v[0:3]
	v_mfma_f32_16x16x32_bf16 v[52:55], v[134:137], v[190:193], v[52:55]
	v_mfma_f32_16x16x32_bf16 v[48:51], v[142:145], v[190:193], v[48:51]
	v_mfma_f32_16x16x32_bf16 v[36:39], v[134:137], v[182:185], v[36:39]
	v_mfma_f32_16x16x32_bf16 v[32:35], v[142:145], v[182:185], v[32:35]
	v_mfma_f32_16x16x32_bf16 v[20:23], v[134:137], v[174:177], v[20:23]
	v_mfma_f32_16x16x32_bf16 v[16:19], v[142:145], v[174:177], v[16:19]
	v_mfma_f32_16x16x32_bf16 v[4:7], v[134:137], v[166:169], v[4:7]
	v_mfma_f32_16x16x32_bf16 v[0:3], v[142:145], v[166:169], v[0:3]
	s_setprio 0
.LBB0_320:
	s_add_u32 s80, s72, 0x80
	s_addc_u32 s81, s73, 0
	s_add_u32 s76, s76, 0x80
	s_addc_u32 s77, s77, 0
	s_barrier
	ds_read_b128 v[146:149], v194 offset:32768
	ds_read_b128 v[150:153], v194 offset:33792
	ds_read_b128 v[154:157], v194 offset:34816
	ds_read_b128 v[158:161], v194 offset:35840
	ds_read_b128 v[130:133], v194 offset:49152
	ds_read_b128 v[134:137], v194 offset:50176
	ds_read_b128 v[138:141], v194 offset:51200
	ds_read_b128 v[142:145], v194 offset:52224
	s_add_u32 s72, s72, s9
	s_addc_u32 s73, s73, 0
	s_mov_b32 s95, m0
	s_mov_b32 m0, s20
	s_nop 0
	global_load_lds_dwordx4 v245, s[72:73]
	s_mov_b32 m0, s95
	s_nop 0
	s_mov_b32 s95, m0
	s_mov_b32 m0, s21
	s_nop 0
	global_load_lds_dwordx4 v247, s[72:73]
	s_mov_b32 m0, s95
	s_waitcnt lgkmcnt(0)
	ds_read_b128 v[162:165], v252 offset:32768
	ds_read_b128 v[166:169], v252 offset:33792
	ds_read_b128 v[170:173], v252 offset:34816
	ds_read_b128 v[174:177], v252 offset:35840
	ds_read_b128 v[178:181], v252 offset:36864
	ds_read_b128 v[182:185], v252 offset:37888
	ds_read_b128 v[186:189], v252 offset:38912
	ds_read_b128 v[190:193], v252 offset:39936
	s_waitcnt vmcnt(8) lgkmcnt(0)
	s_setprio 1
	s_barrier
	v_mfma_f32_16x16x32_bf16 v[124:127], v[146:149], v[162:165], v[124:127]
	v_mfma_f32_16x16x32_bf16 v[120:123], v[154:157], v[162:165], v[120:123]
	v_mfma_f32_16x16x32_bf16 v[108:111], v[146:149], v[170:173], v[108:111]
	v_mfma_f32_16x16x32_bf16 v[104:107], v[154:157], v[170:173], v[104:107]
	v_mfma_f32_16x16x32_bf16 v[92:95], v[146:149], v[178:181], v[92:95]
	v_mfma_f32_16x16x32_bf16 v[88:91], v[154:157], v[178:181], v[88:91]
	v_mfma_f32_16x16x32_bf16 v[76:79], v[146:149], v[186:189], v[76:79]
	v_mfma_f32_16x16x32_bf16 v[72:75], v[154:157], v[186:189], v[72:75]
	v_mfma_f32_16x16x32_bf16 v[124:127], v[150:153], v[166:169], v[124:127]
	v_mfma_f32_16x16x32_bf16 v[120:123], v[158:161], v[166:169], v[120:123]
	v_mfma_f32_16x16x32_bf16 v[108:111], v[150:153], v[174:177], v[108:111]
	v_mfma_f32_16x16x32_bf16 v[104:107], v[158:161], v[174:177], v[104:107]
	v_mfma_f32_16x16x32_bf16 v[92:95], v[150:153], v[182:185], v[92:95]
	v_mfma_f32_16x16x32_bf16 v[88:91], v[158:161], v[182:185], v[88:91]
	v_mfma_f32_16x16x32_bf16 v[76:79], v[150:153], v[190:193], v[76:79]
	v_mfma_f32_16x16x32_bf16 v[72:75], v[158:161], v[190:193], v[72:75]
	s_setprio 0
	s_setprio 1
	v_mfma_f32_16x16x32_bf16 v[116:119], v[130:133], v[162:165], v[116:119]
	v_mfma_f32_16x16x32_bf16 v[112:115], v[138:141], v[162:165], v[112:115]
	v_mfma_f32_16x16x32_bf16 v[100:103], v[130:133], v[170:173], v[100:103]
	v_mfma_f32_16x16x32_bf16 v[96:99], v[138:141], v[170:173], v[96:99]
	v_mfma_f32_16x16x32_bf16 v[84:87], v[130:133], v[178:181], v[84:87]
	v_mfma_f32_16x16x32_bf16 v[80:83], v[138:141], v[178:181], v[80:83]
	v_mfma_f32_16x16x32_bf16 v[68:71], v[130:133], v[186:189], v[68:71]
	v_mfma_f32_16x16x32_bf16 v[64:67], v[138:141], v[186:189], v[64:67]
	v_mfma_f32_16x16x32_bf16 v[116:119], v[134:137], v[166:169], v[116:119]
	v_mfma_f32_16x16x32_bf16 v[112:115], v[142:145], v[166:169], v[112:115]
	v_mfma_f32_16x16x32_bf16 v[100:103], v[134:137], v[174:177], v[100:103]
	v_mfma_f32_16x16x32_bf16 v[96:99], v[142:145], v[174:177], v[96:99]
	v_mfma_f32_16x16x32_bf16 v[84:87], v[134:137], v[182:185], v[84:87]
	v_mfma_f32_16x16x32_bf16 v[80:83], v[142:145], v[182:185], v[80:83]
	v_mfma_f32_16x16x32_bf16 v[68:71], v[134:137], v[190:193], v[68:71]
	v_mfma_f32_16x16x32_bf16 v[64:67], v[142:145], v[190:193], v[64:67]
	s_setprio 0
	s_barrier
	s_mov_b32 s72, m0
	s_mov_b32 m0, s23
	s_nop 0
	global_load_lds_dwordx4 v246, s[76:77]
	s_mov_b32 m0, s72
	s_nop 0
	s_mov_b32 s72, m0
	s_mov_b32 m0, s30
	s_nop 0
	global_load_lds_dwordx4 v248, s[76:77]
	s_mov_b32 m0, s72
	s_add_u32 s72, s74, 0x80
	s_addc_u32 s73, s75, 0
	s_mov_b32 s74, m0
	s_mov_b32 m0, s52
	s_nop 0
	global_load_lds_dwordx4 v246, s[72:73]
	s_mov_b32 m0, s74
	s_and_b64 vcc, exec, s[42:43]
	s_mov_b32 s74, m0
	s_mov_b32 m0, s53
	s_nop 0
	global_load_lds_dwordx4 v248, s[72:73]
	s_mov_b32 m0, s74
	s_mov_b32 s72, m0
	s_mov_b32 m0, s47
	s_nop 0
	global_load_lds_dwordx4 v245, s[80:81]
	s_mov_b32 m0, s72
	s_nop 0
	s_mov_b32 s72, m0
	s_mov_b32 m0, s50
	s_nop 0
	global_load_lds_dwordx4 v247, s[80:81]
	s_mov_b32 m0, s72
	ds_read_b128 v[186:189], v252 offset:49152
	ds_read_b128 v[190:193], v252 offset:50176
	ds_read_b128 v[178:181], v252 offset:51200
	ds_read_b128 v[182:185], v252 offset:52224
	ds_read_b128 v[170:173], v252 offset:53248
	ds_read_b128 v[174:177], v252 offset:54272
	ds_read_b128 v[162:165], v252 offset:55296
	ds_read_b128 v[166:169], v252 offset:56320
	s_waitcnt vmcnt(8) lgkmcnt(0)
	s_barrier
	s_cbranch_vccnz .LBB0_317
	s_setprio 1
	v_mfma_f32_16x16x32_bf16 v[60:63], v[146:149], v[186:189], v[60:63]
	v_mfma_f32_16x16x32_bf16 v[56:59], v[154:157], v[186:189], v[56:59]
	v_mfma_f32_16x16x32_bf16 v[44:47], v[146:149], v[178:181], v[44:47]
	v_mfma_f32_16x16x32_bf16 v[40:43], v[154:157], v[178:181], v[40:43]
	v_mfma_f32_16x16x32_bf16 v[28:31], v[146:149], v[170:173], v[28:31]
	v_mfma_f32_16x16x32_bf16 v[24:27], v[154:157], v[170:173], v[24:27]
	v_mfma_f32_16x16x32_bf16 v[12:15], v[146:149], v[162:165], v[12:15]
	v_mfma_f32_16x16x32_bf16 v[8:11], v[154:157], v[162:165], v[8:11]
	v_mfma_f32_16x16x32_bf16 v[60:63], v[150:153], v[190:193], v[60:63]
	v_mfma_f32_16x16x32_bf16 v[56:59], v[158:161], v[190:193], v[56:59]
	v_mfma_f32_16x16x32_bf16 v[44:47], v[150:153], v[182:185], v[44:47]
	v_mfma_f32_16x16x32_bf16 v[40:43], v[158:161], v[182:185], v[40:43]
	v_mfma_f32_16x16x32_bf16 v[28:31], v[150:153], v[174:177], v[28:31]
	v_mfma_f32_16x16x32_bf16 v[24:27], v[158:161], v[174:177], v[24:27]
	v_mfma_f32_16x16x32_bf16 v[12:15], v[150:153], v[166:169], v[12:15]
	v_mfma_f32_16x16x32_bf16 v[8:11], v[158:161], v[166:169], v[8:11]
	s_setprio 0
	s_setprio 1
	v_mfma_f32_16x16x32_bf16 v[52:55], v[130:133], v[186:189], v[52:55]
	v_mfma_f32_16x16x32_bf16 v[48:51], v[138:141], v[186:189], v[48:51]
	v_mfma_f32_16x16x32_bf16 v[36:39], v[130:133], v[178:181], v[36:39]
	v_mfma_f32_16x16x32_bf16 v[32:35], v[138:141], v[178:181], v[32:35]
	v_mfma_f32_16x16x32_bf16 v[20:23], v[130:133], v[170:173], v[20:23]
	v_mfma_f32_16x16x32_bf16 v[16:19], v[138:141], v[170:173], v[16:19]
	v_mfma_f32_16x16x32_bf16 v[4:7], v[130:133], v[162:165], v[4:7]
	v_mfma_f32_16x16x32_bf16 v[0:3], v[138:141], v[162:165], v[0:3]
	v_mfma_f32_16x16x32_bf16 v[52:55], v[134:137], v[190:193], v[52:55]
	v_mfma_f32_16x16x32_bf16 v[48:51], v[142:145], v[190:193], v[48:51]
	v_mfma_f32_16x16x32_bf16 v[36:39], v[134:137], v[182:185], v[36:39]
	v_mfma_f32_16x16x32_bf16 v[32:35], v[142:145], v[182:185], v[32:35]
	v_mfma_f32_16x16x32_bf16 v[20:23], v[134:137], v[174:177], v[20:23]
	v_mfma_f32_16x16x32_bf16 v[16:19], v[142:145], v[174:177], v[16:19]
	v_mfma_f32_16x16x32_bf16 v[4:7], v[134:137], v[166:169], v[4:7]
	v_mfma_f32_16x16x32_bf16 v[0:3], v[142:145], v[166:169], v[0:3]
	s_setprio 0
	s_branch .LBB0_317

.LBB0_413:
	ds_read_b128 v[146:149], v210
	ds_read_b128 v[150:153], v210 offset:1024
	ds_read_b128 v[154:157], v210 offset:2048
	ds_read_b128 v[158:161], v210 offset:3072
	ds_read_b128 v[130:133], v210 offset:16384
	ds_read_b128 v[134:137], v210 offset:17408
	ds_read_b128 v[138:141], v210 offset:18432
	ds_read_b128 v[142:145], v210 offset:19456
	s_mov_b32 s38, m0
	s_mov_b32 m0, s30
	s_nop 0
	global_load_lds_dwordx4 v195, s[46:47]
	s_mov_b32 m0, s38
	s_nop 0
	s_mov_b32 s38, m0
	s_mov_b32 m0, s14
	s_nop 0
	global_load_lds_dwordx4 v197, s[46:47]
	s_mov_b32 m0, s38
	s_add_u32 s38, s46, 0xfffc0080
	s_addc_u32 s39, s47, -1
	s_cmp_eq_u32 s19, 12
	s_cselect_b32 s75, s27, s39
	s_cselect_b32 s74, s99, s38
	s_cselect_b32 s63, s23, s18
	s_cselect_b32 s62, s3, s8
	s_waitcnt lgkmcnt(0)
	ds_read_b128 v[162:165], v209
	ds_read_b128 v[166:169], v209 offset:1024
	ds_read_b128 v[170:173], v209 offset:2048
	ds_read_b128 v[174:177], v209 offset:3072
	ds_read_b128 v[178:181], v209 offset:4096
	ds_read_b128 v[182:185], v209 offset:5120
	ds_read_b128 v[186:189], v209 offset:6144
	ds_read_b128 v[190:193], v209 offset:7168
	s_waitcnt vmcnt(8) lgkmcnt(0)
	s_setprio 1
	s_barrier
	v_mfma_f32_16x16x32_bf16 v[124:127], v[146:149], v[162:165], v[124:127]
	v_mfma_f32_16x16x32_bf16 v[120:123], v[154:157], v[162:165], v[120:123]
	v_mfma_f32_16x16x32_bf16 v[108:111], v[146:149], v[170:173], v[108:111]
	v_mfma_f32_16x16x32_bf16 v[104:107], v[154:157], v[170:173], v[104:107]
	v_mfma_f32_16x16x32_bf16 v[92:95], v[146:149], v[178:181], v[92:95]
	v_mfma_f32_16x16x32_bf16 v[88:91], v[154:157], v[178:181], v[88:91]
	v_mfma_f32_16x16x32_bf16 v[76:79], v[146:149], v[186:189], v[76:79]
	v_mfma_f32_16x16x32_bf16 v[72:75], v[154:157], v[186:189], v[72:75]
	v_mfma_f32_16x16x32_bf16 v[124:127], v[150:153], v[166:169], v[124:127]
	v_mfma_f32_16x16x32_bf16 v[120:123], v[158:161], v[166:169], v[120:123]
	v_mfma_f32_16x16x32_bf16 v[108:111], v[150:153], v[174:177], v[108:111]
	v_mfma_f32_16x16x32_bf16 v[104:107], v[158:161], v[174:177], v[104:107]
	v_mfma_f32_16x16x32_bf16 v[92:95], v[150:153], v[182:185], v[92:95]
	v_mfma_f32_16x16x32_bf16 v[88:91], v[158:161], v[182:185], v[88:91]
	v_mfma_f32_16x16x32_bf16 v[76:79], v[150:153], v[190:193], v[76:79]
	v_mfma_f32_16x16x32_bf16 v[72:75], v[158:161], v[190:193], v[72:75]
	s_setprio 0
	s_setprio 1
	v_mfma_f32_16x16x32_bf16 v[116:119], v[130:133], v[162:165], v[116:119]
	v_mfma_f32_16x16x32_bf16 v[112:115], v[138:141], v[162:165], v[112:115]
	v_mfma_f32_16x16x32_bf16 v[100:103], v[130:133], v[170:173], v[100:103]
	v_mfma_f32_16x16x32_bf16 v[96:99], v[138:141], v[170:173], v[96:99]
	v_mfma_f32_16x16x32_bf16 v[84:87], v[130:133], v[178:181], v[84:87]
	v_mfma_f32_16x16x32_bf16 v[80:83], v[138:141], v[178:181], v[80:83]
	v_mfma_f32_16x16x32_bf16 v[68:71], v[130:133], v[186:189], v[68:71]
	v_mfma_f32_16x16x32_bf16 v[64:67], v[138:141], v[186:189], v[64:67]
	v_mfma_f32_16x16x32_bf16 v[116:119], v[134:137], v[166:169], v[116:119]
	v_mfma_f32_16x16x32_bf16 v[112:115], v[142:145], v[166:169], v[112:115]
	v_mfma_f32_16x16x32_bf16 v[100:103], v[134:137], v[174:177], v[100:103]
	v_mfma_f32_16x16x32_bf16 v[96:99], v[142:145], v[174:177], v[96:99]
	v_mfma_f32_16x16x32_bf16 v[84:87], v[134:137], v[182:185], v[84:87]
	v_mfma_f32_16x16x32_bf16 v[80:83], v[142:145], v[182:185], v[80:83]
	v_mfma_f32_16x16x32_bf16 v[68:71], v[134:137], v[190:193], v[68:71]
	v_mfma_f32_16x16x32_bf16 v[64:67], v[142:145], v[190:193], v[64:67]
	s_setprio 0
	s_barrier
	s_mov_b32 s38, m0
	s_mov_b32 m0, s67
	s_nop 0
	global_load_lds_dwordx4 v196, s[62:63]
	s_mov_b32 m0, s38
	s_add_u32 s44, s62, 0x40000
	s_mov_b32 s38, m0
	s_mov_b32 m0, s86
	s_nop 0
	global_load_lds_dwordx4 v198, s[62:63]
	s_mov_b32 m0, s38
	s_addc_u32 s45, s63, 0
	s_mov_b32 s38, m0
	s_mov_b32 m0, s87
	s_nop 0
	global_load_lds_dwordx4 v196, s[44:45]
	s_mov_b32 m0, s38
	v_cndmask_b32_e64 v128, 0, 1, s[72:73]
	s_mov_b32 s38, m0
	s_mov_b32 m0, s88
	s_nop 0
	global_load_lds_dwordx4 v198, s[44:45]
	s_mov_b32 m0, s38
	v_cmp_ne_u32_e64 s[44:45], 1, v128
	s_mov_b32 s38, m0
	s_mov_b32 m0, s51
	s_nop 0
	global_load_lds_dwordx4 v195, s[74:75]
	s_mov_b32 m0, s38
	s_andn2_b64 vcc, exec, s[72:73]
	s_mov_b32 s38, m0
	s_mov_b32 m0, s89
	s_nop 0
	global_load_lds_dwordx4 v197, s[74:75]
	s_mov_b32 m0, s38
	ds_read_b128 v[186:189], v209 offset:16384
	ds_read_b128 v[190:193], v209 offset:17408
	ds_read_b128 v[178:181], v209 offset:18432
	ds_read_b128 v[182:185], v209 offset:19456
	ds_read_b128 v[170:173], v209 offset:20480
	ds_read_b128 v[174:177], v209 offset:21504
	ds_read_b128 v[162:165], v209 offset:22528
	ds_read_b128 v[166:169], v209 offset:23552
	s_waitcnt vmcnt(8) lgkmcnt(0)
	s_barrier
	s_cbranch_vccnz .LBB0_415
	s_setprio 1
	v_mfma_f32_16x16x32_bf16 v[60:63], v[146:149], v[186:189], v[60:63]
	v_mfma_f32_16x16x32_bf16 v[56:59], v[154:157], v[186:189], v[56:59]
	v_mfma_f32_16x16x32_bf16 v[44:47], v[146:149], v[178:181], v[44:47]
	v_mfma_f32_16x16x32_bf16 v[40:43], v[154:157], v[178:181], v[40:43]
	v_mfma_f32_16x16x32_bf16 v[28:31], v[146:149], v[170:173], v[28:31]
	v_mfma_f32_16x16x32_bf16 v[24:27], v[154:157], v[170:173], v[24:27]
	v_mfma_f32_16x16x32_bf16 v[12:15], v[146:149], v[162:165], v[12:15]
	v_mfma_f32_16x16x32_bf16 v[8:11], v[154:157], v[162:165], v[8:11]
	v_mfma_f32_16x16x32_bf16 v[60:63], v[150:153], v[190:193], v[60:63]
	v_mfma_f32_16x16x32_bf16 v[56:59], v[158:161], v[190:193], v[56:59]
	v_mfma_f32_16x16x32_bf16 v[44:47], v[150:153], v[182:185], v[44:47]
	v_mfma_f32_16x16x32_bf16 v[40:43], v[158:161], v[182:185], v[40:43]
	v_mfma_f32_16x16x32_bf16 v[28:31], v[150:153], v[174:177], v[28:31]
	v_mfma_f32_16x16x32_bf16 v[24:27], v[158:161], v[174:177], v[24:27]
	v_mfma_f32_16x16x32_bf16 v[12:15], v[150:153], v[166:169], v[12:15]
	v_mfma_f32_16x16x32_bf16 v[8:11], v[158:161], v[166:169], v[8:11]
	s_setprio 0
	s_setprio 1
	v_mfma_f32_16x16x32_bf16 v[52:55], v[130:133], v[186:189], v[52:55]
	v_mfma_f32_16x16x32_bf16 v[48:51], v[138:141], v[186:189], v[48:51]
	v_mfma_f32_16x16x32_bf16 v[36:39], v[130:133], v[178:181], v[36:39]
	v_mfma_f32_16x16x32_bf16 v[32:35], v[138:141], v[178:181], v[32:35]
	v_mfma_f32_16x16x32_bf16 v[20:23], v[130:133], v[170:173], v[20:23]
	v_mfma_f32_16x16x32_bf16 v[16:19], v[138:141], v[170:173], v[16:19]
	v_mfma_f32_16x16x32_bf16 v[4:7], v[130:133], v[162:165], v[4:7]
	v_mfma_f32_16x16x32_bf16 v[0:3], v[138:141], v[162:165], v[0:3]
	v_mfma_f32_16x16x32_bf16 v[52:55], v[134:137], v[190:193], v[52:55]
	v_mfma_f32_16x16x32_bf16 v[48:51], v[142:145], v[190:193], v[48:51]
	v_mfma_f32_16x16x32_bf16 v[36:39], v[134:137], v[182:185], v[36:39]
	v_mfma_f32_16x16x32_bf16 v[32:35], v[142:145], v[182:185], v[32:35]
	v_mfma_f32_16x16x32_bf16 v[20:23], v[134:137], v[174:177], v[20:23]
	v_mfma_f32_16x16x32_bf16 v[16:19], v[142:145], v[174:177], v[16:19]
	v_mfma_f32_16x16x32_bf16 v[4:7], v[134:137], v[166:169], v[4:7]
	v_mfma_f32_16x16x32_bf16 v[0:3], v[142:145], v[166:169], v[0:3]
	s_setprio 0
.LBB0_415:
	s_add_u32 s76, s74, 0x80
	s_addc_u32 s77, s75, 0
	s_add_u32 s38, s62, 0x80
	s_addc_u32 s39, s63, 0
	s_barrier
	ds_read_b128 v[146:149], v210 offset:32768
	ds_read_b128 v[150:153], v210 offset:33792
	ds_read_b128 v[154:157], v210 offset:34816
	ds_read_b128 v[158:161], v210 offset:35840
	ds_read_b128 v[130:133], v210 offset:49152
	ds_read_b128 v[134:137], v210 offset:50176
	ds_read_b128 v[138:141], v210 offset:51200
	ds_read_b128 v[142:145], v210 offset:52224
	s_add_u32 s74, s74, 0x40000
	s_addc_u32 s75, s75, 0
	s_mov_b32 vcc_lo, m0
	s_mov_b32 m0, s92
	s_nop 0
	global_load_lds_dwordx4 v195, s[74:75]
	s_mov_b32 m0, vcc_lo
	s_nop 0
	s_mov_b32 vcc_lo, m0
	s_mov_b32 m0, s93
	s_nop 0
	global_load_lds_dwordx4 v197, s[74:75]
	s_mov_b32 m0, vcc_lo
	s_waitcnt lgkmcnt(0)
	ds_read_b128 v[162:165], v209 offset:32768
	ds_read_b128 v[166:169], v209 offset:33792
	ds_read_b128 v[170:173], v209 offset:34816
	ds_read_b128 v[174:177], v209 offset:35840
	ds_read_b128 v[178:181], v209 offset:36864
	ds_read_b128 v[182:185], v209 offset:37888
	ds_read_b128 v[186:189], v209 offset:38912
	ds_read_b128 v[190:193], v209 offset:39936
	s_waitcnt vmcnt(8) lgkmcnt(0)
	s_setprio 1
	s_barrier
	v_mfma_f32_16x16x32_bf16 v[124:127], v[146:149], v[162:165], v[124:127]
	v_mfma_f32_16x16x32_bf16 v[120:123], v[154:157], v[162:165], v[120:123]
	v_mfma_f32_16x16x32_bf16 v[108:111], v[146:149], v[170:173], v[108:111]
	v_mfma_f32_16x16x32_bf16 v[104:107], v[154:157], v[170:173], v[104:107]
	v_mfma_f32_16x16x32_bf16 v[92:95], v[146:149], v[178:181], v[92:95]
	v_mfma_f32_16x16x32_bf16 v[88:91], v[154:157], v[178:181], v[88:91]
	v_mfma_f32_16x16x32_bf16 v[76:79], v[146:149], v[186:189], v[76:79]
	v_mfma_f32_16x16x32_bf16 v[72:75], v[154:157], v[186:189], v[72:75]
	v_mfma_f32_16x16x32_bf16 v[124:127], v[150:153], v[166:169], v[124:127]
	v_mfma_f32_16x16x32_bf16 v[120:123], v[158:161], v[166:169], v[120:123]
	v_mfma_f32_16x16x32_bf16 v[108:111], v[150:153], v[174:177], v[108:111]
	v_mfma_f32_16x16x32_bf16 v[104:107], v[158:161], v[174:177], v[104:107]
	v_mfma_f32_16x16x32_bf16 v[92:95], v[150:153], v[182:185], v[92:95]
	v_mfma_f32_16x16x32_bf16 v[88:91], v[158:161], v[182:185], v[88:91]
	v_mfma_f32_16x16x32_bf16 v[76:79], v[150:153], v[190:193], v[76:79]
	v_mfma_f32_16x16x32_bf16 v[72:75], v[158:161], v[190:193], v[72:75]
	s_setprio 0
	s_setprio 1
	v_mfma_f32_16x16x32_bf16 v[116:119], v[130:133], v[162:165], v[116:119]
	v_mfma_f32_16x16x32_bf16 v[112:115], v[138:141], v[162:165], v[112:115]
	v_mfma_f32_16x16x32_bf16 v[100:103], v[130:133], v[170:173], v[100:103]
	v_mfma_f32_16x16x32_bf16 v[96:99], v[138:141], v[170:173], v[96:99]
	v_mfma_f32_16x16x32_bf16 v[84:87], v[130:133], v[178:181], v[84:87]
	v_mfma_f32_16x16x32_bf16 v[80:83], v[138:141], v[178:181], v[80:83]
	v_mfma_f32_16x16x32_bf16 v[68:71], v[130:133], v[186:189], v[68:71]
	v_mfma_f32_16x16x32_bf16 v[64:67], v[138:141], v[186:189], v[64:67]
	v_mfma_f32_16x16x32_bf16 v[116:119], v[134:137], v[166:169], v[116:119]
	v_mfma_f32_16x16x32_bf16 v[112:115], v[142:145], v[166:169], v[112:115]
	v_mfma_f32_16x16x32_bf16 v[100:103], v[134:137], v[174:177], v[100:103]
	v_mfma_f32_16x16x32_bf16 v[96:99], v[142:145], v[174:177], v[96:99]
	v_mfma_f32_16x16x32_bf16 v[84:87], v[134:137], v[182:185], v[84:87]
	v_mfma_f32_16x16x32_bf16 v[80:83], v[142:145], v[182:185], v[80:83]
	v_mfma_f32_16x16x32_bf16 v[68:71], v[134:137], v[190:193], v[68:71]
	v_mfma_f32_16x16x32_bf16 v[64:67], v[142:145], v[190:193], v[64:67]
	s_setprio 0
	s_barrier
	s_mov_b32 s74, m0
	s_mov_b32 m0, s95
	s_nop 0
	global_load_lds_dwordx4 v196, s[38:39]
	s_mov_b32 m0, s74
	s_nop 0
	s_mov_b32 s74, m0
	s_mov_b32 m0, s96
	s_nop 0
	global_load_lds_dwordx4 v198, s[38:39]
	s_mov_b32 m0, s74
	s_add_u32 s38, s62, 0x40080
	s_addc_u32 s39, s63, 0
	s_mov_b32 s62, m0
	s_mov_b32 m0, s65
	s_nop 0
	global_load_lds_dwordx4 v196, s[38:39]
	s_mov_b32 m0, s62
	s_and_b64 vcc, exec, s[44:45]
	s_mov_b32 s62, m0
	s_mov_b32 m0, s50
	s_nop 0
	global_load_lds_dwordx4 v198, s[38:39]
	s_mov_b32 m0, s62
	s_mov_b32 s38, m0
	s_mov_b32 m0, s97
	s_nop 0
	global_load_lds_dwordx4 v195, s[76:77]
	s_mov_b32 m0, s38
	s_nop 0
	s_mov_b32 s38, m0
	s_mov_b32 m0, s9
	s_nop 0
	global_load_lds_dwordx4 v197, s[76:77]
	s_mov_b32 m0, s38
	ds_read_b128 v[186:189], v209 offset:49152
	ds_read_b128 v[190:193], v209 offset:50176
	ds_read_b128 v[178:181], v209 offset:51200
	ds_read_b128 v[182:185], v209 offset:52224
	ds_read_b128 v[170:173], v209 offset:53248
	ds_read_b128 v[174:177], v209 offset:54272
	ds_read_b128 v[162:165], v209 offset:55296
	ds_read_b128 v[166:169], v209 offset:56320
	s_waitcnt vmcnt(8) lgkmcnt(0)
	s_barrier
	s_cbranch_vccnz .LBB0_412
	s_setprio 1
	v_mfma_f32_16x16x32_bf16 v[60:63], v[146:149], v[186:189], v[60:63]
	v_mfma_f32_16x16x32_bf16 v[56:59], v[154:157], v[186:189], v[56:59]
	v_mfma_f32_16x16x32_bf16 v[44:47], v[146:149], v[178:181], v[44:47]
	v_mfma_f32_16x16x32_bf16 v[40:43], v[154:157], v[178:181], v[40:43]
	v_mfma_f32_16x16x32_bf16 v[28:31], v[146:149], v[170:173], v[28:31]
	v_mfma_f32_16x16x32_bf16 v[24:27], v[154:157], v[170:173], v[24:27]
	v_mfma_f32_16x16x32_bf16 v[12:15], v[146:149], v[162:165], v[12:15]
	v_mfma_f32_16x16x32_bf16 v[8:11], v[154:157], v[162:165], v[8:11]
	v_mfma_f32_16x16x32_bf16 v[60:63], v[150:153], v[190:193], v[60:63]
	v_mfma_f32_16x16x32_bf16 v[56:59], v[158:161], v[190:193], v[56:59]
	v_mfma_f32_16x16x32_bf16 v[44:47], v[150:153], v[182:185], v[44:47]
	v_mfma_f32_16x16x32_bf16 v[40:43], v[158:161], v[182:185], v[40:43]
	v_mfma_f32_16x16x32_bf16 v[28:31], v[150:153], v[174:177], v[28:31]
	v_mfma_f32_16x16x32_bf16 v[24:27], v[158:161], v[174:177], v[24:27]
	v_mfma_f32_16x16x32_bf16 v[12:15], v[150:153], v[166:169], v[12:15]
	v_mfma_f32_16x16x32_bf16 v[8:11], v[158:161], v[166:169], v[8:11]
	s_setprio 0
	s_setprio 1
	v_mfma_f32_16x16x32_bf16 v[52:55], v[130:133], v[186:189], v[52:55]
	v_mfma_f32_16x16x32_bf16 v[48:51], v[138:141], v[186:189], v[48:51]
	v_mfma_f32_16x16x32_bf16 v[36:39], v[130:133], v[178:181], v[36:39]
	v_mfma_f32_16x16x32_bf16 v[32:35], v[138:141], v[178:181], v[32:35]
	v_mfma_f32_16x16x32_bf16 v[20:23], v[130:133], v[170:173], v[20:23]
	v_mfma_f32_16x16x32_bf16 v[16:19], v[138:141], v[170:173], v[16:19]
	v_mfma_f32_16x16x32_bf16 v[4:7], v[130:133], v[162:165], v[4:7]
	v_mfma_f32_16x16x32_bf16 v[0:3], v[138:141], v[162:165], v[0:3]
	v_mfma_f32_16x16x32_bf16 v[52:55], v[134:137], v[190:193], v[52:55]
	v_mfma_f32_16x16x32_bf16 v[48:51], v[142:145], v[190:193], v[48:51]
	v_mfma_f32_16x16x32_bf16 v[36:39], v[134:137], v[182:185], v[36:39]
	v_mfma_f32_16x16x32_bf16 v[32:35], v[142:145], v[182:185], v[32:35]
	v_mfma_f32_16x16x32_bf16 v[20:23], v[134:137], v[174:177], v[20:23]
	v_mfma_f32_16x16x32_bf16 v[16:19], v[142:145], v[174:177], v[16:19]
	v_mfma_f32_16x16x32_bf16 v[4:7], v[134:137], v[166:169], v[4:7]
	v_mfma_f32_16x16x32_bf16 v[0:3], v[142:145], v[166:169], v[0:3]
	s_setprio 0
	s_branch .LBB0_412
